# rope tables spread over 3 workgroups; MLA up-projection epilogue pre-touches the per-row ssq records so the serialized per-row loads hit L1
# baseline (speedup 1.0000x reference)
;     __device__ __forceinline__ void operator()(const f32x4 (&acc)[2][2][4][2], const Unit& u, int wr_in, int wc_in, int fr_in, int fq_in) const {
;     ...
;             for (int m = 0; m < 4; ++m) {
;                 const int row = u.pm * 256 + ai * 128 + wr * 64 + 4 * fr + m;
;                 const float* sp = ssq + (size_t)row * 20;
;                 const f32x4 p0 = *(const f32x4*)(sp), p1 = *(const f32x4*)(sp + 4);
;                 float ss = (p0[0] + p0[1]) + (p0[2] + p0[3]) + (p1[0] + p1[1]) + (p1[2] + p1[3]);
;                 if (nslot == 12) { const f32x4 p2 = *(const f32x4*)(sp + 8); ss += (p2[0] + p2[1]) + (p2[2] + p2[3]); }
;                 const float rs = sc / sqrtf(ss * invn + RMS_EPS);
.LBB0_190:
	v_mov_b32_e32 v162, v155
	s_mov_b32 s13, s63
	v_mov_b32_e32 v0, v156
	s_mov_b32 s0, s59
	s_lshl_b32 s1, s12, 8
	s_lshl_b32 s0, s0, 6
	v_lshlrev_b32_e32 v0, 2, v0
	s_add_i32 s0, s0, s1
	v_add_u32_e32 v160, s0, v0
	v_mov_b64_e32 v[142:143], s[86:87]
	v_mad_i64_i32 v[144:145], s[0:1], v160, s26, v[142:143]
	flat_load_dwordx4 v[146:149], v[144:145]
	flat_load_dwordx4 v[150:153], v[144:145] offset:16
	global_load_dwordx4 v[184:187], v[144:145], off offset:80
	global_load_dwordx4 v[184:187], v[144:145], off offset:144
	global_load_dwordx4 v[184:187], v[144:145], off offset:160
	global_load_dwordx4 v[184:187], v[144:145], off offset:224
	global_load_dwordx4 v[184:187], v[144:145], off offset:240
	global_load_dwordx4 v[184:187], v[144:145], off offset:304
	s_mov_b64 s[16:17], 0x2800
	v_lshl_add_u64 v[188:189], s[16:17], 0, v[144:145]
	global_load_dwordx4 v[184:187], v[188:189], off offset:0
	global_load_dwordx4 v[184:187], v[188:189], off offset:64
	global_load_dwordx4 v[184:187], v[188:189], off offset:80
	global_load_dwordx4 v[184:187], v[188:189], off offset:144
	global_load_dwordx4 v[184:187], v[188:189], off offset:160
	global_load_dwordx4 v[184:187], v[188:189], off offset:224
	global_load_dwordx4 v[184:187], v[188:189], off offset:240
	global_load_dwordx4 v[184:187], v[188:189], off offset:304
	s_mov_b64 s[48:49], 0
	s_andn2_b64 vcc, exec, s[6:7]
	s_mov_b64 s[0:1], 0
	s_waitcnt vmcnt(0) lgkmcnt(0)
	v_mov_b32_e32 v142, v147
	v_mov_b32_e32 v143, v148
	v_mov_b32_e32 v147, v149
	v_pk_add_f32 v[142:143], v[142:143], v[146:147]
	v_mov_b32_e32 v146, v152
	v_mov_b32_e32 v147, v150
	v_mov_b32_e32 v150, v153
	v_pk_add_f32 v[142:143], v[142:143], v[142:143] op_sel:[0,1] op_sel_hi:[1,0]
	v_pk_add_f32 v[146:147], v[146:147], v[150:151]
	s_nop 0
	v_pk_add_f32 v[142:143], v[142:143], v[146:147] op_sel:[0,1] op_sel_hi:[1,0]
	s_nop 0
	v_pk_add_f32 v[142:143], v[146:147], v[142:143]
	s_nop 0
	v_cndmask_b32_e64 v143, 0, 1, s[6:7]
	v_cmp_ne_u32_e64 s[42:43], 1, v143
	s_cbranch_vccnz .LBB0_192
	flat_load_dwordx4 v[144:147], v[144:145] offset:32
	s_cmpk_lt_i32 s12, 0x80
	s_cselect_b64 s[0:1], -1, 0
	s_waitcnt vmcnt(0) lgkmcnt(0)
	v_mov_b32_e32 v148, v145
	v_mov_b32_e32 v149, v146
	v_mov_b32_e32 v145, v147
	v_pk_add_f32 v[144:145], v[148:149], v[144:145]
	s_nop 0
	v_add_f32_e32 v143, v144, v145
	v_add_f32_e32 v142, v142, v143
